# P8+P9 fused, score tile transposed through LDS (XOR-swizzled) so every global store writes full 128-B lines of the key-major score layout
# speedup vs baseline: 1.0171x; 1.0081x over previous
; DI unsigned pack2bf(float a, float b) { const f2_t v = {a, b}; return __builtin_bit_cast(unsigned, __builtin_convertvector(v, bf2_t)); }
; template <class Epi>
; DI void gemm_tile256(const u16* __restrict__ Ag, long lda, const u16* __restrict__ Bg, long ldb, int nk, char* shm, Epi&& epi) {
;     ...
;   __syncthreads();
; #pragma unroll
;   for (int m = 0; m < 8; ++m)
; #pragma unroll
;     for (int n = 0; n < 4; ++n) epi(wr * 128 + m * 16 + fr, wc * 64 + n * 16 + fq * 4, acc[m][n]);
; DI void phase8(const Params& P, char* smem) {
;     ...
;     gemm_tile256(h1b + (long)brow * 1024, 1024, WqT + (long)bcol * 1024, 1024, 32, smem, [&](int row, int col0, f32x4 v) {
;       *reinterpret_cast<uint2*>(Qp + (long)(brow + row) * 2048 + bcol + col0) = make_uint2(pack2bf(v[0], v[1]), pack2bf(v[2], v[3]));
;     });
.Lgemm_p8_kend:
	s_nop 7
	s_nop 3
	s_waitcnt vmcnt(0) lgkmcnt(0)
	s_barrier
	v_and_b32_e32 v186, 15, v208
	v_lshrrev_b32_e32 v187, 4, v208
	v_lshrrev_b32_e32 v206, 6, v189
	v_lshlrev_b32_e32 v206, 14, v206
	v_and_b32_e32 v207, 7, v186
	v_lshrrev_b32_e32 v224, 1, v187
	v_and_b32_e32 v225, 1, v187
	v_lshl_add_u32 v226, v186, 7, v206
	v_lshl_add_u32 v226, v225, 3, v226
	v_or_b32_e32 v227, 0, v224
	v_xor_b32_e32 v227, v227, v207
	v_lshl_add_u32 v232, v227, 4, v226
	v_or_b32_e32 v227, 2, v224
	v_xor_b32_e32 v227, v227, v207
	v_lshl_add_u32 v233, v227, 4, v226
	v_or_b32_e32 v227, 4, v224
	v_xor_b32_e32 v227, v227, v207
	v_lshl_add_u32 v234, v227, 4, v226
	v_or_b32_e32 v227, 6, v224
	v_xor_b32_e32 v227, v227, v207
	v_lshl_add_u32 v235, v227, 4, v226
	v_lshrrev_b32_e32 v228, 3, v208
	v_and_b32_e32 v229, 7, v208
	v_xor_b32_e32 v227, v229, v228
	v_lshl_add_u32 v236, v228, 7, v206
	v_lshl_add_u32 v236, v227, 4, v236
	v_lshl_add_u32 v227, v190, 7, v228
	v_add_u32_e32 v227, s10, v227
	v_lshlrev_b32_e32 v238, 12, v227
	v_bfe_u32 v227, v189, 6, 2
	v_lshl_add_u32 v238, v227, 7, v238
	v_lshl_add_u32 v238, v229, 4, v238
	v_mov_b32_e32 v239, 0
	s_and_b32 s26, s74, 7
	s_lshl_b32 s26, s26, 9
	s_add_u32 s26, s26, 0x8000000
	s_add_u32 s26, s78, s26
	s_addc_u32 s27, s79, 0
	v_lshl_add_u64 v[238:239], v[238:239], 0, s[26:27]
	s_mov_b32 s28, 0x8000
	s_mov_b32 s29, 0
	v_lshl_add_u64 v[240:241], v[238:239], 0, s[28:29]
	s_lshl_b32 s28, s28, 1
	v_cvt_pk_bf16_f32 v124, v124, v125
	v_cvt_pk_bf16_f32 v125, v126, v127
	ds_write_b64 v232, v[124:125] offset:0
	v_cvt_pk_bf16_f32 v120, v120, v121
	v_cvt_pk_bf16_f32 v121, v122, v123
	ds_write_b64 v233, v[120:121] offset:0
	v_cvt_pk_bf16_f32 v116, v116, v117
	v_cvt_pk_bf16_f32 v117, v118, v119
	ds_write_b64 v234, v[116:117] offset:0
	v_cvt_pk_bf16_f32 v112, v112, v113
	v_cvt_pk_bf16_f32 v113, v114, v115
	ds_write_b64 v235, v[112:113] offset:0
	v_cvt_pk_bf16_f32 v108, v108, v109
	v_cvt_pk_bf16_f32 v109, v110, v111
	ds_write_b64 v232, v[108:109] offset:2048
	v_cvt_pk_bf16_f32 v104, v104, v105
	v_cvt_pk_bf16_f32 v105, v106, v107
	ds_write_b64 v233, v[104:105] offset:2048
	v_cvt_pk_bf16_f32 v100, v100, v101
	v_cvt_pk_bf16_f32 v101, v102, v103
	ds_write_b64 v234, v[100:101] offset:2048
	v_cvt_pk_bf16_f32 v96, v96, v97
	v_cvt_pk_bf16_f32 v97, v98, v99
	ds_write_b64 v235, v[96:97] offset:2048
	v_cvt_pk_bf16_f32 v92, v92, v93
	v_cvt_pk_bf16_f32 v93, v94, v95
	ds_write_b64 v232, v[92:93] offset:4096
	v_cvt_pk_bf16_f32 v88, v88, v89
	v_cvt_pk_bf16_f32 v89, v90, v91
	ds_write_b64 v233, v[88:89] offset:4096
	v_cvt_pk_bf16_f32 v84, v84, v85
	v_cvt_pk_bf16_f32 v85, v86, v87
	ds_write_b64 v234, v[84:85] offset:4096
	v_cvt_pk_bf16_f32 v80, v80, v81
	v_cvt_pk_bf16_f32 v81, v82, v83
	ds_write_b64 v235, v[80:81] offset:4096
	v_cvt_pk_bf16_f32 v76, v76, v77
	v_cvt_pk_bf16_f32 v77, v78, v79
	ds_write_b64 v232, v[76:77] offset:6144
	v_cvt_pk_bf16_f32 v72, v72, v73
	v_cvt_pk_bf16_f32 v73, v74, v75
	ds_write_b64 v233, v[72:73] offset:6144
	v_cvt_pk_bf16_f32 v68, v68, v69
	v_cvt_pk_bf16_f32 v69, v70, v71
	ds_write_b64 v234, v[68:69] offset:6144
	v_cvt_pk_bf16_f32 v64, v64, v65
	v_cvt_pk_bf16_f32 v65, v66, v67
	ds_write_b64 v235, v[64:65] offset:6144
	v_cvt_pk_bf16_f32 v60, v60, v61
	v_cvt_pk_bf16_f32 v61, v62, v63
	ds_write_b64 v232, v[60:61] offset:8192
	v_cvt_pk_bf16_f32 v56, v56, v57
	v_cvt_pk_bf16_f32 v57, v58, v59
	ds_write_b64 v233, v[56:57] offset:8192
	v_cvt_pk_bf16_f32 v52, v52, v53
	v_cvt_pk_bf16_f32 v53, v54, v55
	ds_write_b64 v234, v[52:53] offset:8192
	v_cvt_pk_bf16_f32 v48, v48, v49
	v_cvt_pk_bf16_f32 v49, v50, v51
	ds_write_b64 v235, v[48:49] offset:8192
	v_cvt_pk_bf16_f32 v44, v44, v45
	v_cvt_pk_bf16_f32 v45, v46, v47
	ds_write_b64 v232, v[44:45] offset:10240
	v_cvt_pk_bf16_f32 v40, v40, v41
	v_cvt_pk_bf16_f32 v41, v42, v43
	ds_write_b64 v233, v[40:41] offset:10240
	v_cvt_pk_bf16_f32 v36, v36, v37
	v_cvt_pk_bf16_f32 v37, v38, v39
	ds_write_b64 v234, v[36:37] offset:10240
	v_cvt_pk_bf16_f32 v32, v32, v33
	v_cvt_pk_bf16_f32 v33, v34, v35
	ds_write_b64 v235, v[32:33] offset:10240
	v_cvt_pk_bf16_f32 v28, v28, v29
	v_cvt_pk_bf16_f32 v29, v30, v31
	ds_write_b64 v232, v[28:29] offset:12288
	v_cvt_pk_bf16_f32 v24, v24, v25
	v_cvt_pk_bf16_f32 v25, v26, v27
	ds_write_b64 v233, v[24:25] offset:12288
	v_cvt_pk_bf16_f32 v20, v20, v21
	v_cvt_pk_bf16_f32 v21, v22, v23
	ds_write_b64 v234, v[20:21] offset:12288
	v_cvt_pk_bf16_f32 v16, v16, v17
	v_cvt_pk_bf16_f32 v17, v18, v19
	ds_write_b64 v235, v[16:17] offset:12288
	v_cvt_pk_bf16_f32 v12, v12, v13
	v_cvt_pk_bf16_f32 v13, v14, v15
	ds_write_b64 v232, v[12:13] offset:14336
	v_cvt_pk_bf16_f32 v8, v8, v9
	v_cvt_pk_bf16_f32 v9, v10, v11
	ds_write_b64 v233, v[8:9] offset:14336
	v_cvt_pk_bf16_f32 v4, v4, v5
	v_cvt_pk_bf16_f32 v5, v6, v7
	ds_write_b64 v234, v[4:5] offset:14336
	v_cvt_pk_bf16_f32 v0, v0, v1
	v_cvt_pk_bf16_f32 v1, v2, v3
	ds_write_b64 v235, v[0:1] offset:14336
	s_waitcnt lgkmcnt(0)
	s_barrier
; #define TILE_LOOP(tile, N, C)                                                                                          \
;   for (int q0_ = (RBLK >> 3) * 2, tile = 0;                                                                            \
;        q0_ < (N) / 8 && ((tile = xcd_tile((q0_ + VHALF < (N) / 8 ? q0_ + VHALF : q0_), RBLK & 7, (C))), true);          \
;        q0_ += (RGRID >> 3) * 2)
; DI void phase9(const Params& P, char* smem) {
;     ...
;   TILE_LOOP(tile, 256 * 16, 16) {
;     const int brow = (tile >> 4) * 128, hc = tile & 15;
;     gemm_tile<false>(Qp + (long)brow * 2048 + hc * 128, 2048, SKb + (long)hc * 128 * 128, 128, 0, 2, 0, 0, smem, [&](int row0, int col, f32x4 v) {
;       typedef _Float16 h4 __attribute__((ext_vector_type(4)));
;       h4 hv; hv[0] = (_Float16)v[0]; hv[1] = (_Float16)v[1]; hv[2] = (_Float16)v[2]; hv[3] = (_Float16)v[3];
;       *reinterpret_cast<h4*>(ST + ((long)(hc * 128 + col)) * NTOK + brow + row0) = hv;
;     });
	v_lshrrev_b32_e32 v224, 6, v189
	v_lshrrev_b32_e32 v225, 2, v224
	v_and_b32_e32 v226, 3, v224
	v_lshlrev_b32_e32 v225, 16, v225
	v_lshl_add_u32 v226, v226, 5, v186
	v_lshl_add_u32 v225, v226, 7, v225
	v_and_b32_e32 v227, 7, v186
	v_xor_b32_e32 v227, v227, v187
	v_lshl_add_u32 v232, v227, 4, v225
	v_xor_b32_e32 v227, 4, v227
	v_lshl_add_u32 v233, v227, 4, v225
	ds_read_b128 v[0:3], v232 offset:0
	ds_read_b128 v[4:7], v233 offset:0
	ds_read_b128 v[8:11], v232 offset:16384
	ds_read_b128 v[12:15], v233 offset:16384
	ds_read_b128 v[16:19], v232 offset:32768
	ds_read_b128 v[20:23], v233 offset:32768
	ds_read_b128 v[24:27], v232 offset:49152
	ds_read_b128 v[28:31], v233 offset:49152
	ds_read_b128 v[32:35], v232 offset:2048
	ds_read_b128 v[36:39], v233 offset:2048
	ds_read_b128 v[40:43], v232 offset:18432
	ds_read_b128 v[44:47], v233 offset:18432
	ds_read_b128 v[48:51], v232 offset:34816
	ds_read_b128 v[52:55], v233 offset:34816
	ds_read_b128 v[56:59], v232 offset:51200
	ds_read_b128 v[60:63], v233 offset:51200
	s_and_b32 s26, s74, 7
	s_lshl_b32 s26, s26, 16
	s_add_u32 s26, s26, 0x18a80000
	s_add_u32 s26, s78, s26
	s_addc_u32 s27, s79, 0
	v_lshlrev_b32_e32 v234, 8, v186
	v_lshl_add_u32 v234, v187, 4, v234
	s_and_b32 s28, s74, 7
	s_cmp_lt_u32 s28, 4
	s_cselect_b32 s29, 0x6000000, 0
	s_sub_u32 s29, 0x10000000, s29
	s_lshl_b32 s28, s28, 24
	s_add_u32 s28, s28, s29
	s_add_u32 s28, s78, s28
	s_addc_u32 s29, s79, 0
	v_lshrrev_b32_e32 v226, 1, v187
	v_lshl_add_u32 v226, v224, 2, v226
	v_xor_b32_e32 v226, v226, v186
	v_and_b32_e32 v227, 1, v187
	v_lshlrev_b32_e32 v227, 3, v227
	v_lshl_add_u32 v227, v226, 4, v227
	v_lshl_add_u32 v236, v186, 9, v227
	v_lshrrev_b32_e32 v226, 5, v208
	v_and_b32_e32 v227, 31, v208
	v_lshl_add_u32 v225, v224, 5, v226
	v_xor_b32_e32 v226, v227, v226
	v_lshlrev_b32_e32 v226, 4, v226
	v_lshl_add_u32 v240, v225, 9, v226
	s_lshl_b32 s10, s10, 1
	v_lshl_add_u32 v241, v227, 4, s10
	s_lshr_b32 s10, s10, 1
	v_lshl_add_u32 v241, v225, 16, v241
	v_add_u32_e32 v235, 0x0, v234
	global_load_dwordx4 v[64:67], v235, s[26:27] offset:0
	global_load_dwordx4 v[68:71], v235, s[26:27] offset:64
	global_load_dwordx4 v[72:75], v235, s[26:27] offset:128
	global_load_dwordx4 v[76:79], v235, s[26:27] offset:192
	v_add_u32_e32 v235, 0x1000, v234
	global_load_dwordx4 v[80:83], v235, s[26:27] offset:0
	global_load_dwordx4 v[84:87], v235, s[26:27] offset:64
	global_load_dwordx4 v[88:91], v235, s[26:27] offset:128
	global_load_dwordx4 v[92:95], v235, s[26:27] offset:192
	s_waitcnt lgkmcnt(0)
	s_barrier
	s_waitcnt vmcnt(4)
	v_mfma_f32_16x16x32_bf16 v[96:99], v[0:3], v[64:67], 0
	v_mfma_f32_16x16x32_bf16 v[96:99], v[4:7], v[68:71], v[96:99]
	v_mfma_f32_16x16x32_bf16 v[96:99], v[8:11], v[72:75], v[96:99]
	v_mfma_f32_16x16x32_bf16 v[96:99], v[12:15], v[76:79], v[96:99]
	v_mfma_f32_16x16x32_bf16 v[100:103], v[32:35], v[64:67], 0
	v_mfma_f32_16x16x32_bf16 v[100:103], v[36:39], v[68:71], v[100:103]
	v_mfma_f32_16x16x32_bf16 v[100:103], v[40:43], v[72:75], v[100:103]
	v_mfma_f32_16x16x32_bf16 v[100:103], v[44:47], v[76:79], v[100:103]
	v_add_u32_e32 v238, 0x0, v236
	v_xor_b32_e32 v239, 32, v238
	s_nop 7
	s_nop 1
	v_cvt_pk_f16_f32 v104, v96, v97
	v_cvt_pk_f16_f32 v105, v98, v99
	v_cvt_pk_f16_f32 v106, v100, v101
	v_cvt_pk_f16_f32 v107, v102, v103
	ds_write_b64 v238, v[104:105]
	ds_write_b64 v239, v[106:107]
	v_add_u32_e32 v235, 0x2000, v234
	global_load_dwordx4 v[64:67], v235, s[26:27] offset:0
	global_load_dwordx4 v[68:71], v235, s[26:27] offset:64
	global_load_dwordx4 v[72:75], v235, s[26:27] offset:128
	global_load_dwordx4 v[76:79], v235, s[26:27] offset:192
	s_waitcnt vmcnt(4)
	v_mfma_f32_16x16x32_bf16 v[96:99], v[0:3], v[80:83], 0
	v_mfma_f32_16x16x32_bf16 v[96:99], v[4:7], v[84:87], v[96:99]
	v_mfma_f32_16x16x32_bf16 v[96:99], v[8:11], v[88:91], v[96:99]
	v_mfma_f32_16x16x32_bf16 v[96:99], v[12:15], v[92:95], v[96:99]
	v_mfma_f32_16x16x32_bf16 v[100:103], v[32:35], v[80:83], 0
	v_mfma_f32_16x16x32_bf16 v[100:103], v[36:39], v[84:87], v[100:103]
	v_mfma_f32_16x16x32_bf16 v[100:103], v[40:43], v[88:91], v[100:103]
	v_mfma_f32_16x16x32_bf16 v[100:103], v[44:47], v[92:95], v[100:103]
	v_add_u32_e32 v238, 0x2000, v236
	v_xor_b32_e32 v239, 32, v238
	s_nop 7
	s_nop 1
	v_cvt_pk_f16_f32 v104, v96, v97
	v_cvt_pk_f16_f32 v105, v98, v99
	v_cvt_pk_f16_f32 v106, v100, v101
	v_cvt_pk_f16_f32 v107, v102, v103
	ds_write_b64 v238, v[104:105]
	ds_write_b64 v239, v[106:107]
	v_add_u32_e32 v235, 0x3000, v234
	global_load_dwordx4 v[80:83], v235, s[26:27] offset:0
	global_load_dwordx4 v[84:87], v235, s[26:27] offset:64
	global_load_dwordx4 v[88:91], v235, s[26:27] offset:128
	global_load_dwordx4 v[92:95], v235, s[26:27] offset:192
	s_waitcnt vmcnt(4)
	v_mfma_f32_16x16x32_bf16 v[96:99], v[0:3], v[64:67], 0
	v_mfma_f32_16x16x32_bf16 v[96:99], v[4:7], v[68:71], v[96:99]
	v_mfma_f32_16x16x32_bf16 v[96:99], v[8:11], v[72:75], v[96:99]
	v_mfma_f32_16x16x32_bf16 v[96:99], v[12:15], v[76:79], v[96:99]
	v_mfma_f32_16x16x32_bf16 v[100:103], v[32:35], v[64:67], 0
	v_mfma_f32_16x16x32_bf16 v[100:103], v[36:39], v[68:71], v[100:103]
	v_mfma_f32_16x16x32_bf16 v[100:103], v[40:43], v[72:75], v[100:103]
	v_mfma_f32_16x16x32_bf16 v[100:103], v[44:47], v[76:79], v[100:103]
	v_add_u32_e32 v238, 0x4000, v236
	v_xor_b32_e32 v239, 32, v238
	s_nop 7
	s_nop 1
	v_cvt_pk_f16_f32 v104, v96, v97
	v_cvt_pk_f16_f32 v105, v98, v99
	v_cvt_pk_f16_f32 v106, v100, v101
	v_cvt_pk_f16_f32 v107, v102, v103
	ds_write_b64 v238, v[104:105]
	ds_write_b64 v239, v[106:107]
	v_add_u32_e32 v235, 0x4000, v234
	global_load_dwordx4 v[64:67], v235, s[26:27] offset:0
	global_load_dwordx4 v[68:71], v235, s[26:27] offset:64
	global_load_dwordx4 v[72:75], v235, s[26:27] offset:128
	global_load_dwordx4 v[76:79], v235, s[26:27] offset:192
	s_waitcnt vmcnt(4)
; #define TILE_LOOP(tile, N, C)                                                                                          \
;   for (int q0_ = (RBLK >> 3) * 2, tile = 0;                                                                            \
;        q0_ < (N) / 8 && ((tile = xcd_tile((q0_ + VHALF < (N) / 8 ? q0_ + VHALF : q0_), RBLK & 7, (C))), true);          \
;        q0_ += (RGRID >> 3) * 2)
; DI void phase9(const Params& P, char* smem) {
;     ...
;   TILE_LOOP(tile, 256 * 16, 16) {
;     const int brow = (tile >> 4) * 128, hc = tile & 15;
;     gemm_tile<false>(Qp + (long)brow * 2048 + hc * 128, 2048, SKb + (long)hc * 128 * 128, 128, 0, 2, 0, 0, smem, [&](int row0, int col, f32x4 v) {
;       typedef _Float16 h4 __attribute__((ext_vector_type(4)));
;       h4 hv; hv[0] = (_Float16)v[0]; hv[1] = (_Float16)v[1]; hv[2] = (_Float16)v[2]; hv[3] = (_Float16)v[3];
;       *reinterpret_cast<h4*>(ST + ((long)(hc * 128 + col)) * NTOK + brow + row0) = hv;
;     });
	v_mfma_f32_16x16x32_bf16 v[96:99], v[0:3], v[80:83], 0
	v_mfma_f32_16x16x32_bf16 v[96:99], v[4:7], v[84:87], v[96:99]
	v_mfma_f32_16x16x32_bf16 v[96:99], v[8:11], v[88:91], v[96:99]
	v_mfma_f32_16x16x32_bf16 v[96:99], v[12:15], v[92:95], v[96:99]
	v_mfma_f32_16x16x32_bf16 v[100:103], v[32:35], v[80:83], 0
	v_mfma_f32_16x16x32_bf16 v[100:103], v[36:39], v[84:87], v[100:103]
	v_mfma_f32_16x16x32_bf16 v[100:103], v[40:43], v[88:91], v[100:103]
	v_mfma_f32_16x16x32_bf16 v[100:103], v[44:47], v[92:95], v[100:103]
	v_add_u32_e32 v238, 0x6000, v236
	v_xor_b32_e32 v239, 32, v238
	s_nop 7
	s_nop 1
	v_cvt_pk_f16_f32 v104, v96, v97
	v_cvt_pk_f16_f32 v105, v98, v99
	v_cvt_pk_f16_f32 v106, v100, v101
	v_cvt_pk_f16_f32 v107, v102, v103
	ds_write_b64 v238, v[104:105]
	ds_write_b64 v239, v[106:107]
	v_add_u32_e32 v235, 0x5000, v234
	global_load_dwordx4 v[80:83], v235, s[26:27] offset:0
	global_load_dwordx4 v[84:87], v235, s[26:27] offset:64
	global_load_dwordx4 v[88:91], v235, s[26:27] offset:128
	global_load_dwordx4 v[92:95], v235, s[26:27] offset:192
	s_waitcnt vmcnt(4)
	v_mfma_f32_16x16x32_bf16 v[96:99], v[0:3], v[64:67], 0
	v_mfma_f32_16x16x32_bf16 v[96:99], v[4:7], v[68:71], v[96:99]
	v_mfma_f32_16x16x32_bf16 v[96:99], v[8:11], v[72:75], v[96:99]
	v_mfma_f32_16x16x32_bf16 v[96:99], v[12:15], v[76:79], v[96:99]
	v_mfma_f32_16x16x32_bf16 v[100:103], v[32:35], v[64:67], 0
	v_mfma_f32_16x16x32_bf16 v[100:103], v[36:39], v[68:71], v[100:103]
	v_mfma_f32_16x16x32_bf16 v[100:103], v[40:43], v[72:75], v[100:103]
	v_mfma_f32_16x16x32_bf16 v[100:103], v[44:47], v[76:79], v[100:103]
	v_add_u32_e32 v238, 0x8000, v236
	v_xor_b32_e32 v239, 32, v238
	s_nop 7
	s_nop 1
	v_cvt_pk_f16_f32 v104, v96, v97
	v_cvt_pk_f16_f32 v105, v98, v99
	v_cvt_pk_f16_f32 v106, v100, v101
	v_cvt_pk_f16_f32 v107, v102, v103
	ds_write_b64 v238, v[104:105]
	ds_write_b64 v239, v[106:107]
	v_add_u32_e32 v235, 0x6000, v234
	global_load_dwordx4 v[64:67], v235, s[26:27] offset:0
	global_load_dwordx4 v[68:71], v235, s[26:27] offset:64
	global_load_dwordx4 v[72:75], v235, s[26:27] offset:128
	global_load_dwordx4 v[76:79], v235, s[26:27] offset:192
	s_waitcnt vmcnt(4)
	v_mfma_f32_16x16x32_bf16 v[96:99], v[0:3], v[80:83], 0
	v_mfma_f32_16x16x32_bf16 v[96:99], v[4:7], v[84:87], v[96:99]
	v_mfma_f32_16x16x32_bf16 v[96:99], v[8:11], v[88:91], v[96:99]
	v_mfma_f32_16x16x32_bf16 v[96:99], v[12:15], v[92:95], v[96:99]
	v_mfma_f32_16x16x32_bf16 v[100:103], v[32:35], v[80:83], 0
	v_mfma_f32_16x16x32_bf16 v[100:103], v[36:39], v[84:87], v[100:103]
	v_mfma_f32_16x16x32_bf16 v[100:103], v[40:43], v[88:91], v[100:103]
	v_mfma_f32_16x16x32_bf16 v[100:103], v[44:47], v[92:95], v[100:103]
	v_add_u32_e32 v238, 0xa000, v236
	v_xor_b32_e32 v239, 32, v238
	s_nop 7
	s_nop 1
	v_cvt_pk_f16_f32 v104, v96, v97
	v_cvt_pk_f16_f32 v105, v98, v99
	v_cvt_pk_f16_f32 v106, v100, v101
	v_cvt_pk_f16_f32 v107, v102, v103
	ds_write_b64 v238, v[104:105]
	ds_write_b64 v239, v[106:107]
	v_add_u32_e32 v235, 0x7000, v234
	global_load_dwordx4 v[80:83], v235, s[26:27] offset:0
	global_load_dwordx4 v[84:87], v235, s[26:27] offset:64
	global_load_dwordx4 v[88:91], v235, s[26:27] offset:128
	global_load_dwordx4 v[92:95], v235, s[26:27] offset:192
	s_waitcnt vmcnt(4)
	v_mfma_f32_16x16x32_bf16 v[96:99], v[0:3], v[64:67], 0
	v_mfma_f32_16x16x32_bf16 v[96:99], v[4:7], v[68:71], v[96:99]
	v_mfma_f32_16x16x32_bf16 v[96:99], v[8:11], v[72:75], v[96:99]
	v_mfma_f32_16x16x32_bf16 v[96:99], v[12:15], v[76:79], v[96:99]
	v_mfma_f32_16x16x32_bf16 v[100:103], v[32:35], v[64:67], 0
	v_mfma_f32_16x16x32_bf16 v[100:103], v[36:39], v[68:71], v[100:103]
	v_mfma_f32_16x16x32_bf16 v[100:103], v[40:43], v[72:75], v[100:103]
	v_mfma_f32_16x16x32_bf16 v[100:103], v[44:47], v[76:79], v[100:103]
	v_add_u32_e32 v238, 0xc000, v236
	v_xor_b32_e32 v239, 32, v238
	s_nop 7
	s_nop 1
	v_cvt_pk_f16_f32 v104, v96, v97
	v_cvt_pk_f16_f32 v105, v98, v99
	v_cvt_pk_f16_f32 v106, v100, v101
	v_cvt_pk_f16_f32 v107, v102, v103
	ds_write_b64 v238, v[104:105]
	ds_write_b64 v239, v[106:107]
	v_add_u32_e32 v235, 0x8000, v234
	global_load_dwordx4 v[64:67], v235, s[26:27] offset:0
	global_load_dwordx4 v[68:71], v235, s[26:27] offset:64
	global_load_dwordx4 v[72:75], v235, s[26:27] offset:128
	global_load_dwordx4 v[76:79], v235, s[26:27] offset:192
	s_waitcnt vmcnt(4)
	v_mfma_f32_16x16x32_bf16 v[96:99], v[0:3], v[80:83], 0
	v_mfma_f32_16x16x32_bf16 v[96:99], v[4:7], v[84:87], v[96:99]
	v_mfma_f32_16x16x32_bf16 v[96:99], v[8:11], v[88:91], v[96:99]
	v_mfma_f32_16x16x32_bf16 v[96:99], v[12:15], v[92:95], v[96:99]
	v_mfma_f32_16x16x32_bf16 v[100:103], v[32:35], v[80:83], 0
	v_mfma_f32_16x16x32_bf16 v[100:103], v[36:39], v[84:87], v[100:103]
	v_mfma_f32_16x16x32_bf16 v[100:103], v[40:43], v[88:91], v[100:103]
	v_mfma_f32_16x16x32_bf16 v[100:103], v[44:47], v[92:95], v[100:103]
	v_add_u32_e32 v238, 0xe000, v236
	v_xor_b32_e32 v239, 32, v238
	s_nop 7
	s_nop 1
	v_cvt_pk_f16_f32 v104, v96, v97
	v_cvt_pk_f16_f32 v105, v98, v99
	v_cvt_pk_f16_f32 v106, v100, v101
	v_cvt_pk_f16_f32 v107, v102, v103
	ds_write_b64 v238, v[104:105]
	ds_write_b64 v239, v[106:107]
	v_add_u32_e32 v235, 0x9000, v234
	global_load_dwordx4 v[80:83], v235, s[26:27] offset:0
	global_load_dwordx4 v[84:87], v235, s[26:27] offset:64
	global_load_dwordx4 v[88:91], v235, s[26:27] offset:128
	global_load_dwordx4 v[92:95], v235, s[26:27] offset:192
	s_waitcnt vmcnt(4)
; #define TILE_LOOP(tile, N, C)                                                                                          \
;   for (int q0_ = (RBLK >> 3) * 2, tile = 0;                                                                            \
;        q0_ < (N) / 8 && ((tile = xcd_tile((q0_ + VHALF < (N) / 8 ? q0_ + VHALF : q0_), RBLK & 7, (C))), true);          \
;        q0_ += (RGRID >> 3) * 2)
; DI void phase9(const Params& P, char* smem) {
;     ...
;   TILE_LOOP(tile, 256 * 16, 16) {
;     const int brow = (tile >> 4) * 128, hc = tile & 15;
;     gemm_tile<false>(Qp + (long)brow * 2048 + hc * 128, 2048, SKb + (long)hc * 128 * 128, 128, 0, 2, 0, 0, smem, [&](int row0, int col, f32x4 v) {
;       typedef _Float16 h4 __attribute__((ext_vector_type(4)));
;       h4 hv; hv[0] = (_Float16)v[0]; hv[1] = (_Float16)v[1]; hv[2] = (_Float16)v[2]; hv[3] = (_Float16)v[3];
;       *reinterpret_cast<h4*>(ST + ((long)(hc * 128 + col)) * NTOK + brow + row0) = hv;
;     });
	v_mfma_f32_16x16x32_bf16 v[96:99], v[16:19], v[64:67], 0
	v_mfma_f32_16x16x32_bf16 v[96:99], v[20:23], v[68:71], v[96:99]
	v_mfma_f32_16x16x32_bf16 v[96:99], v[24:27], v[72:75], v[96:99]
	v_mfma_f32_16x16x32_bf16 v[96:99], v[28:31], v[76:79], v[96:99]
	v_mfma_f32_16x16x32_bf16 v[100:103], v[48:51], v[64:67], 0
	v_mfma_f32_16x16x32_bf16 v[100:103], v[52:55], v[68:71], v[100:103]
	v_mfma_f32_16x16x32_bf16 v[100:103], v[56:59], v[72:75], v[100:103]
	v_mfma_f32_16x16x32_bf16 v[100:103], v[60:63], v[76:79], v[100:103]
	v_add_u32_e32 v238, 0x10000, v236
	v_xor_b32_e32 v239, 32, v238
	s_nop 7
	s_nop 1
	v_cvt_pk_f16_f32 v104, v96, v97
	v_cvt_pk_f16_f32 v105, v98, v99
	v_cvt_pk_f16_f32 v106, v100, v101
	v_cvt_pk_f16_f32 v107, v102, v103
	ds_write_b64 v238, v[104:105]
	ds_write_b64 v239, v[106:107]
	v_add_u32_e32 v235, 0xa000, v234
	global_load_dwordx4 v[64:67], v235, s[26:27] offset:0
	global_load_dwordx4 v[68:71], v235, s[26:27] offset:64
	global_load_dwordx4 v[72:75], v235, s[26:27] offset:128
	global_load_dwordx4 v[76:79], v235, s[26:27] offset:192
	s_waitcnt vmcnt(4)
	v_mfma_f32_16x16x32_bf16 v[96:99], v[16:19], v[80:83], 0
	v_mfma_f32_16x16x32_bf16 v[96:99], v[20:23], v[84:87], v[96:99]
	v_mfma_f32_16x16x32_bf16 v[96:99], v[24:27], v[88:91], v[96:99]
	v_mfma_f32_16x16x32_bf16 v[96:99], v[28:31], v[92:95], v[96:99]
	v_mfma_f32_16x16x32_bf16 v[100:103], v[48:51], v[80:83], 0
	v_mfma_f32_16x16x32_bf16 v[100:103], v[52:55], v[84:87], v[100:103]
	v_mfma_f32_16x16x32_bf16 v[100:103], v[56:59], v[88:91], v[100:103]
	v_mfma_f32_16x16x32_bf16 v[100:103], v[60:63], v[92:95], v[100:103]
	v_add_u32_e32 v238, 0x12000, v236
	v_xor_b32_e32 v239, 32, v238
	s_nop 7
	s_nop 1
	v_cvt_pk_f16_f32 v104, v96, v97
	v_cvt_pk_f16_f32 v105, v98, v99
	v_cvt_pk_f16_f32 v106, v100, v101
	v_cvt_pk_f16_f32 v107, v102, v103
	ds_write_b64 v238, v[104:105]
	ds_write_b64 v239, v[106:107]
	v_add_u32_e32 v235, 0xb000, v234
	global_load_dwordx4 v[80:83], v235, s[26:27] offset:0
	global_load_dwordx4 v[84:87], v235, s[26:27] offset:64
	global_load_dwordx4 v[88:91], v235, s[26:27] offset:128
	global_load_dwordx4 v[92:95], v235, s[26:27] offset:192
	s_waitcnt vmcnt(4)
	v_mfma_f32_16x16x32_bf16 v[96:99], v[16:19], v[64:67], 0
	v_mfma_f32_16x16x32_bf16 v[96:99], v[20:23], v[68:71], v[96:99]
	v_mfma_f32_16x16x32_bf16 v[96:99], v[24:27], v[72:75], v[96:99]
	v_mfma_f32_16x16x32_bf16 v[96:99], v[28:31], v[76:79], v[96:99]
	v_mfma_f32_16x16x32_bf16 v[100:103], v[48:51], v[64:67], 0
	v_mfma_f32_16x16x32_bf16 v[100:103], v[52:55], v[68:71], v[100:103]
	v_mfma_f32_16x16x32_bf16 v[100:103], v[56:59], v[72:75], v[100:103]
	v_mfma_f32_16x16x32_bf16 v[100:103], v[60:63], v[76:79], v[100:103]
	v_add_u32_e32 v238, 0x14000, v236
	v_xor_b32_e32 v239, 32, v238
	s_nop 7
	s_nop 1
	v_cvt_pk_f16_f32 v104, v96, v97
	v_cvt_pk_f16_f32 v105, v98, v99
	v_cvt_pk_f16_f32 v106, v100, v101
	v_cvt_pk_f16_f32 v107, v102, v103
	ds_write_b64 v238, v[104:105]
	ds_write_b64 v239, v[106:107]
	v_add_u32_e32 v235, 0xc000, v234
	global_load_dwordx4 v[64:67], v235, s[26:27] offset:0
	global_load_dwordx4 v[68:71], v235, s[26:27] offset:64
	global_load_dwordx4 v[72:75], v235, s[26:27] offset:128
	global_load_dwordx4 v[76:79], v235, s[26:27] offset:192
	s_waitcnt vmcnt(4)
	v_mfma_f32_16x16x32_bf16 v[96:99], v[16:19], v[80:83], 0
	v_mfma_f32_16x16x32_bf16 v[96:99], v[20:23], v[84:87], v[96:99]
	v_mfma_f32_16x16x32_bf16 v[96:99], v[24:27], v[88:91], v[96:99]
	v_mfma_f32_16x16x32_bf16 v[96:99], v[28:31], v[92:95], v[96:99]
	v_mfma_f32_16x16x32_bf16 v[100:103], v[48:51], v[80:83], 0
	v_mfma_f32_16x16x32_bf16 v[100:103], v[52:55], v[84:87], v[100:103]
	v_mfma_f32_16x16x32_bf16 v[100:103], v[56:59], v[88:91], v[100:103]
	v_mfma_f32_16x16x32_bf16 v[100:103], v[60:63], v[92:95], v[100:103]
	v_add_u32_e32 v238, 0x16000, v236
	v_xor_b32_e32 v239, 32, v238
	s_nop 7
	s_nop 1
	v_cvt_pk_f16_f32 v104, v96, v97
	v_cvt_pk_f16_f32 v105, v98, v99
	v_cvt_pk_f16_f32 v106, v100, v101
	v_cvt_pk_f16_f32 v107, v102, v103
	ds_write_b64 v238, v[104:105]
	ds_write_b64 v239, v[106:107]
	v_add_u32_e32 v235, 0xd000, v234
	global_load_dwordx4 v[80:83], v235, s[26:27] offset:0
	global_load_dwordx4 v[84:87], v235, s[26:27] offset:64
	global_load_dwordx4 v[88:91], v235, s[26:27] offset:128
	global_load_dwordx4 v[92:95], v235, s[26:27] offset:192
	s_waitcnt vmcnt(4)
	v_mfma_f32_16x16x32_bf16 v[96:99], v[16:19], v[64:67], 0
	v_mfma_f32_16x16x32_bf16 v[96:99], v[20:23], v[68:71], v[96:99]
	v_mfma_f32_16x16x32_bf16 v[96:99], v[24:27], v[72:75], v[96:99]
	v_mfma_f32_16x16x32_bf16 v[96:99], v[28:31], v[76:79], v[96:99]
	v_mfma_f32_16x16x32_bf16 v[100:103], v[48:51], v[64:67], 0
	v_mfma_f32_16x16x32_bf16 v[100:103], v[52:55], v[68:71], v[100:103]
	v_mfma_f32_16x16x32_bf16 v[100:103], v[56:59], v[72:75], v[100:103]
	v_mfma_f32_16x16x32_bf16 v[100:103], v[60:63], v[76:79], v[100:103]
	v_add_u32_e32 v238, 0x18000, v236
	v_xor_b32_e32 v239, 32, v238
	s_nop 7
	s_nop 1
	v_cvt_pk_f16_f32 v104, v96, v97
	v_cvt_pk_f16_f32 v105, v98, v99
	v_cvt_pk_f16_f32 v106, v100, v101
	v_cvt_pk_f16_f32 v107, v102, v103
	ds_write_b64 v238, v[104:105]
	ds_write_b64 v239, v[106:107]
	v_add_u32_e32 v235, 0xe000, v234
	global_load_dwordx4 v[64:67], v235, s[26:27] offset:0
	global_load_dwordx4 v[68:71], v235, s[26:27] offset:64
	global_load_dwordx4 v[72:75], v235, s[26:27] offset:128
	global_load_dwordx4 v[76:79], v235, s[26:27] offset:192
	s_waitcnt vmcnt(4)
; #define TILE_LOOP(tile, N, C)                                                                                          \
;   for (int q0_ = (RBLK >> 3) * 2, tile = 0;                                                                            \
;        q0_ < (N) / 8 && ((tile = xcd_tile((q0_ + VHALF < (N) / 8 ? q0_ + VHALF : q0_), RBLK & 7, (C))), true);          \
;        q0_ += (RGRID >> 3) * 2)
; DI void phase9(const Params& P, char* smem) {
;     ...
;   TILE_LOOP(tile, 256 * 16, 16) {
;     const int brow = (tile >> 4) * 128, hc = tile & 15;
;     gemm_tile<false>(Qp + (long)brow * 2048 + hc * 128, 2048, SKb + (long)hc * 128 * 128, 128, 0, 2, 0, 0, smem, [&](int row0, int col, f32x4 v) {
;       typedef _Float16 h4 __attribute__((ext_vector_type(4)));
;       h4 hv; hv[0] = (_Float16)v[0]; hv[1] = (_Float16)v[1]; hv[2] = (_Float16)v[2]; hv[3] = (_Float16)v[3];
;       *reinterpret_cast<h4*>(ST + ((long)(hc * 128 + col)) * NTOK + brow + row0) = hv;
;     });
	v_mfma_f32_16x16x32_bf16 v[96:99], v[16:19], v[80:83], 0
	v_mfma_f32_16x16x32_bf16 v[96:99], v[20:23], v[84:87], v[96:99]
	v_mfma_f32_16x16x32_bf16 v[96:99], v[24:27], v[88:91], v[96:99]
	v_mfma_f32_16x16x32_bf16 v[96:99], v[28:31], v[92:95], v[96:99]
	v_mfma_f32_16x16x32_bf16 v[100:103], v[48:51], v[80:83], 0
	v_mfma_f32_16x16x32_bf16 v[100:103], v[52:55], v[84:87], v[100:103]
	v_mfma_f32_16x16x32_bf16 v[100:103], v[56:59], v[88:91], v[100:103]
	v_mfma_f32_16x16x32_bf16 v[100:103], v[60:63], v[92:95], v[100:103]
	v_add_u32_e32 v238, 0x1a000, v236
	v_xor_b32_e32 v239, 32, v238
	s_nop 7
	s_nop 1
	v_cvt_pk_f16_f32 v104, v96, v97
	v_cvt_pk_f16_f32 v105, v98, v99
	v_cvt_pk_f16_f32 v106, v100, v101
	v_cvt_pk_f16_f32 v107, v102, v103
	ds_write_b64 v238, v[104:105]
	ds_write_b64 v239, v[106:107]
	v_add_u32_e32 v235, 0xf000, v234
	global_load_dwordx4 v[80:83], v235, s[26:27] offset:0
	global_load_dwordx4 v[84:87], v235, s[26:27] offset:64
	global_load_dwordx4 v[88:91], v235, s[26:27] offset:128
	global_load_dwordx4 v[92:95], v235, s[26:27] offset:192
	s_waitcnt vmcnt(4)
	v_mfma_f32_16x16x32_bf16 v[96:99], v[16:19], v[64:67], 0
	v_mfma_f32_16x16x32_bf16 v[96:99], v[20:23], v[68:71], v[96:99]
	v_mfma_f32_16x16x32_bf16 v[96:99], v[24:27], v[72:75], v[96:99]
	v_mfma_f32_16x16x32_bf16 v[96:99], v[28:31], v[76:79], v[96:99]
	v_mfma_f32_16x16x32_bf16 v[100:103], v[48:51], v[64:67], 0
	v_mfma_f32_16x16x32_bf16 v[100:103], v[52:55], v[68:71], v[100:103]
	v_mfma_f32_16x16x32_bf16 v[100:103], v[56:59], v[72:75], v[100:103]
	v_mfma_f32_16x16x32_bf16 v[100:103], v[60:63], v[76:79], v[100:103]
	v_add_u32_e32 v238, 0x1c000, v236
	v_xor_b32_e32 v239, 32, v238
	s_nop 7
	s_nop 1
	v_cvt_pk_f16_f32 v104, v96, v97
	v_cvt_pk_f16_f32 v105, v98, v99
	v_cvt_pk_f16_f32 v106, v100, v101
	v_cvt_pk_f16_f32 v107, v102, v103
	ds_write_b64 v238, v[104:105]
	ds_write_b64 v239, v[106:107]
	s_waitcnt vmcnt(0)
	v_mfma_f32_16x16x32_bf16 v[96:99], v[16:19], v[80:83], 0
	v_mfma_f32_16x16x32_bf16 v[96:99], v[20:23], v[84:87], v[96:99]
	v_mfma_f32_16x16x32_bf16 v[96:99], v[24:27], v[88:91], v[96:99]
	v_mfma_f32_16x16x32_bf16 v[96:99], v[28:31], v[92:95], v[96:99]
	v_mfma_f32_16x16x32_bf16 v[100:103], v[48:51], v[80:83], 0
	v_mfma_f32_16x16x32_bf16 v[100:103], v[52:55], v[84:87], v[100:103]
	v_mfma_f32_16x16x32_bf16 v[100:103], v[56:59], v[88:91], v[100:103]
	v_mfma_f32_16x16x32_bf16 v[100:103], v[60:63], v[92:95], v[100:103]
	v_add_u32_e32 v238, 0x1e000, v236
	v_xor_b32_e32 v239, 32, v238
	s_nop 7
	s_nop 1
	v_cvt_pk_f16_f32 v104, v96, v97
	v_cvt_pk_f16_f32 v105, v98, v99
	v_cvt_pk_f16_f32 v106, v100, v101
	v_cvt_pk_f16_f32 v107, v102, v103
	ds_write_b64 v238, v[104:105]
	ds_write_b64 v239, v[106:107]
	s_waitcnt lgkmcnt(0)
	s_barrier
	v_xor_b32_e32 v238, 0x0, v240
	ds_read_b128 v[64:67], v238 offset:0
	v_xor_b32_e32 v238, 0x20, v240
	ds_read_b128 v[68:71], v238 offset:1024
	v_xor_b32_e32 v238, 0x40, v240
	ds_read_b128 v[72:75], v238 offset:2048
	v_xor_b32_e32 v238, 0x60, v240
	ds_read_b128 v[76:79], v238 offset:3072
	v_xor_b32_e32 v238, 0x80, v240
	ds_read_b128 v[80:83], v238 offset:4096
	v_xor_b32_e32 v238, 0xa0, v240
	ds_read_b128 v[84:87], v238 offset:5120
	v_xor_b32_e32 v238, 0xc0, v240
	ds_read_b128 v[88:91], v238 offset:6144
	v_xor_b32_e32 v238, 0xe0, v240
	ds_read_b128 v[92:95], v238 offset:7168
	s_waitcnt lgkmcnt(7)
	v_add_u32_e32 v239, 0x0, v241
	global_store_dwordx4 v239, v[64:67], s[28:29]
	s_waitcnt lgkmcnt(6)
	v_add_u32_e32 v239, 0x20000, v241
	global_store_dwordx4 v239, v[68:71], s[28:29]
	s_waitcnt lgkmcnt(5)
	v_add_u32_e32 v239, 0x40000, v241
	global_store_dwordx4 v239, v[72:75], s[28:29]
	s_waitcnt lgkmcnt(4)
	v_add_u32_e32 v239, 0x60000, v241
	global_store_dwordx4 v239, v[76:79], s[28:29]
	s_waitcnt lgkmcnt(3)
	v_add_u32_e32 v239, 0x80000, v241
	global_store_dwordx4 v239, v[80:83], s[28:29]
	s_waitcnt lgkmcnt(2)
	v_add_u32_e32 v239, 0xa0000, v241
	global_store_dwordx4 v239, v[84:87], s[28:29]
	s_waitcnt lgkmcnt(1)
	v_add_u32_e32 v239, 0xc0000, v241
	global_store_dwordx4 v239, v[88:91], s[28:29]
	s_waitcnt lgkmcnt(0)
	v_add_u32_e32 v239, 0xe0000, v241
	global_store_dwordx4 v239, v[92:95], s[28:29]
	v_xor_b32_e32 v238, 0x0, v240
	ds_read_b128 v[64:67], v238 offset:8192
	v_xor_b32_e32 v238, 0x20, v240
	ds_read_b128 v[68:71], v238 offset:9216
	v_xor_b32_e32 v238, 0x40, v240
	ds_read_b128 v[72:75], v238 offset:10240
	v_xor_b32_e32 v238, 0x60, v240
	ds_read_b128 v[76:79], v238 offset:11264
	v_xor_b32_e32 v238, 0x80, v240
	ds_read_b128 v[80:83], v238 offset:12288
	v_xor_b32_e32 v238, 0xa0, v240
	ds_read_b128 v[84:87], v238 offset:13312
	v_xor_b32_e32 v238, 0xc0, v240
	ds_read_b128 v[88:91], v238 offset:14336
	v_xor_b32_e32 v238, 0xe0, v240
	ds_read_b128 v[92:95], v238 offset:15360
	s_waitcnt lgkmcnt(7)
	v_add_u32_e32 v239, 0x100000, v241
	global_store_dwordx4 v239, v[64:67], s[28:29]
	s_waitcnt lgkmcnt(6)
	v_add_u32_e32 v239, 0x120000, v241
	global_store_dwordx4 v239, v[68:71], s[28:29]
	s_waitcnt lgkmcnt(5)
	v_add_u32_e32 v239, 0x140000, v241
	global_store_dwordx4 v239, v[72:75], s[28:29]
	s_waitcnt lgkmcnt(4)
	v_add_u32_e32 v239, 0x160000, v241
	global_store_dwordx4 v239, v[76:79], s[28:29]
	s_waitcnt lgkmcnt(3)
	v_add_u32_e32 v239, 0x180000, v241
	global_store_dwordx4 v239, v[80:83], s[28:29]
	s_waitcnt lgkmcnt(2)
	v_add_u32_e32 v239, 0x1a0000, v241
	global_store_dwordx4 v239, v[84:87], s[28:29]
	s_waitcnt lgkmcnt(1)
	v_add_u32_e32 v239, 0x1c0000, v241
	global_store_dwordx4 v239, v[88:91], s[28:29]
	s_waitcnt lgkmcnt(0)
	v_add_u32_e32 v239, 0x1e0000, v241
	global_store_dwordx4 v239, v[92:95], s[28:29]
	s_barrier
	s_add_i32 s75, s75, s5
	s_add_i32 s6, s6, s8
	s_cmpk_lt_i32 s75, 0x80
	s_cbranch_scc1 .LBB0_1068
